# attention loops: scalar branch instead of exec save/restore for the half-workgroup K piece, vmcnt folded into existing lgkmcnt waits
# baseline (speedup 1.0000x reference)
; #define ALAS __attribute__((address_space(3)))
; __device__ __forceinline__ s16x4 vtr(const ALAS unsigned char* p) { return __builtin_bit_cast(s16x4, __builtin_amdgcn_ds_read_tr16_b64_v4i16((ALAS s16x4*)p)); }
; #define AMFMA(a, b, c) __builtin_amdgcn_mfma_f32_32x32x16_bf16((a), (b), (c), 0, 0, 0)
; template <bool SUB> __device__ __forceinline__ void attn_unit_r2(const AU& u, ALAS unsigned char* lds, float mb2) {
;     ...
;         if (t + 1 < NT) { const size_t ro = (size_t)(t + 1) * 64; rk = *(const u32x4*)(kg0 + ro * u.krs); rv = *(const u32x4*)(vg + ro * u.vrs); }
;         {
;             const ALAS unsigned char* kb = lds + cur * KBUF + r * KP + h * 16;
;             const ALAS unsigned char* vb = lds + V_OFF + cur * VBUF + (4 * h + ((lane & 15) >> 2)) * VP + ((lane >> 4) & 1) * 32 + (lane & 3) * 8;
;             f32x16 Sa0 = negm, Sa1 = negm, Sb0 = negm, Sb1 = negm;
; #pragma unroll
;             for (int d0 = 0; d0 < 4; ++d0) {
;                 const bf16x8 k0 = *(const ALAS bf16x8*)(kb + d0 * 32), k1 = *(const ALAS bf16x8*)(kb + 32 * KP + d0 * 32);
;                 Sa0 = AMFMA(k0, qa[d0], Sa0); Sa1 = AMFMA(k1, qa[d0], Sa1); Sb0 = AMFMA(k0, qb[d0], Sb0); Sb1 = AMFMA(k1, qb[d0], Sb1);
;             }
;             bf16x8 paa[4], pab[4];
;     ...
;             R2_SOFT(Sa0, Sa1, paa, la);
;             R2_SOFT(Sb0, Sb1, pab, lb);
;     ...
; #pragma unroll
;             for (int ks = 0; ks < 4; ++ks) {
;                 const s16x4 lo0 = vtr(vb + ks * 16 * VP), hi0 = vtr(vb + (ks * 16 + 8) * VP), lo1 = vtr(vb + ks * 16 * VP + 64), hi1 = vtr(vb + (ks * 16 + 8) * VP + 64);
;                 const bf16x8 vf0 = __builtin_shufflevector(lo0, hi0, 0, 1, 2, 3, 4, 5, 6, 7), vf1 = __builtin_shufflevector(lo1, hi1, 0, 1, 2, 3, 4, 5, 6, 7);
;                 oa0 = AMFMA(paa[ks], vf0, oa0); oa1 = AMFMA(paa[ks], vf1, oa1); ob0 = AMFMA(pab[ks], vf0, ob0); ob1 = AMFMA(pab[ks], vf1, ob1);
.Lr2n_topA:
	global_load_dwordx4 v[128:131], v[174:175], off
	global_load_dwordx4 v[132:135], v[176:177], off
	ds_read_b128 v[222:225], v168 offset:0
	ds_read_b128 v[226:229], v168 offset:32
	ds_read_b128 v[230:233], v168 offset:64
	ds_read_b128 v[234:237], v168 offset:96
	v_mfma_f32_32x32x16_bf16 v[48:63], v[178:181], v[238:241], v[48:63]
	v_add_f32_e32 v172, v96, v172
	v_add_f32_e32 v173, v80, v173
	v_add_f32_e32 v172, v97, v172
	v_add_f32_e32 v173, v81, v173
	v_mfma_f32_32x32x16_bf16 v[64:79], v[178:181], v[248:251], v[64:79]
	v_add_f32_e32 v172, v98, v172
	v_add_f32_e32 v173, v82, v173
	v_add_f32_e32 v172, v99, v172
	v_add_f32_e32 v173, v83, v173
	ds_read_b128 v[178:181], v168 offset:4608
	v_mfma_f32_32x32x16_bf16 v[16:31], v[182:185], v[238:241], v[16:31]
	v_add_f32_e32 v172, v100, v172
	v_add_f32_e32 v173, v84, v173
	v_add_f32_e32 v172, v101, v172
	v_add_f32_e32 v173, v85, v173
	v_mfma_f32_32x32x16_bf16 v[32:47], v[182:185], v[248:251], v[32:47]
	v_add_f32_e32 v172, v102, v172
	v_add_f32_e32 v173, v86, v173
	v_add_f32_e32 v172, v103, v172
	v_add_f32_e32 v173, v87, v173
	ds_read_b128 v[182:185], v168 offset:4640
	v_mfma_f32_32x32x16_bf16 v[48:63], v[186:189], v[194:197], v[48:63]
	v_add_f32_e32 v172, v104, v172
	v_add_f32_e32 v173, v88, v173
	v_add_f32_e32 v172, v105, v172
	v_add_f32_e32 v173, v89, v173
	v_mfma_f32_32x32x16_bf16 v[64:79], v[186:189], v[210:213], v[64:79]
	v_add_f32_e32 v172, v106, v172
	v_add_f32_e32 v173, v90, v173
	v_add_f32_e32 v172, v107, v172
	v_add_f32_e32 v173, v91, v173
	ds_read_b128 v[186:189], v168 offset:4672
	v_mfma_f32_32x32x16_bf16 v[16:31], v[190:193], v[194:197], v[16:31]
	v_add_f32_e32 v172, v108, v172
	v_add_f32_e32 v173, v92, v173
	v_add_f32_e32 v172, v109, v172
	v_add_f32_e32 v173, v93, v173
	v_mfma_f32_32x32x16_bf16 v[32:47], v[190:193], v[210:213], v[32:47]
	v_add_f32_e32 v172, v110, v172
	v_add_f32_e32 v173, v94, v173
	v_add_f32_e32 v172, v111, v172
	v_add_f32_e32 v173, v95, v173
	ds_read_b128 v[190:193], v168 offset:4704
	s_waitcnt lgkmcnt(4)
	v_mfma_f32_32x32x16_bf16 v[96:111], v[222:225], v[136:139], 0
	v_lshl_add_u64 v[174:175], v[174:175], 0, s[12:13]
	v_add_f32_e32 v242, v112, v242
	v_add_f32_e32 v243, v0, v243
	v_add_f32_e32 v242, v113, v242
	v_add_f32_e32 v243, v1, v243
	v_add_f32_e32 v242, v114, v242
	v_mfma_f32_32x32x16_bf16 v[96:111], v[226:229], v[140:143], v[96:111]
	v_lshl_add_u64 v[176:177], v[176:177], 0, s[12:13]
	v_add_f32_e32 v243, v2, v243
	v_add_f32_e32 v242, v115, v242
	v_add_f32_e32 v243, v3, v243
	v_add_f32_e32 v242, v116, v242
	v_add_f32_e32 v243, v4, v243
	v_mfma_f32_32x32x16_bf16 v[96:111], v[230:233], v[144:147], v[96:111]
	v_add_f32_e32 v242, v117, v242
	v_add_f32_e32 v243, v5, v243
	v_add_f32_e32 v242, v118, v242
	v_add_f32_e32 v243, v6, v243
	v_add_f32_e32 v242, v119, v242
	v_add_f32_e32 v243, v7, v243
	v_mfma_f32_32x32x16_bf16 v[96:111], v[234:237], v[148:151], v[96:111]
	v_add_f32_e32 v242, v120, v242
	v_add_f32_e32 v243, v8, v243
	v_add_f32_e32 v242, v121, v242
	v_add_f32_e32 v243, v9, v243
	v_add_f32_e32 v242, v122, v242
	v_add_f32_e32 v243, v10, v243
	v_add_f32_e32 v242, v123, v242
	v_add_f32_e32 v243, v11, v243
	v_mfma_f32_32x32x16_bf16 v[80:95], v[222:225], v[152:155], 0
	v_add_f32_e32 v242, v124, v242
	v_add_f32_e32 v243, v12, v243
	v_add_f32_e32 v242, v125, v242
	v_add_f32_e32 v243, v13, v243
	v_add_f32_e32 v242, v126, v242
	v_add_f32_e32 v243, v14, v243
	v_add_f32_e32 v242, v127, v242
	v_add_f32_e32 v243, v15, v243
	v_mfma_f32_32x32x16_bf16 v[80:95], v[226:229], v[156:159], v[80:95]
	v_exp_f32_e32 v96, v96
	v_exp_f32_e32 v97, v97
	v_exp_f32_e32 v98, v98
	v_exp_f32_e32 v99, v99
	v_mfma_f32_32x32x16_bf16 v[80:95], v[230:233], v[160:163], v[80:95]
	v_exp_f32_e32 v100, v100
	v_exp_f32_e32 v101, v101
	v_exp_f32_e32 v102, v102
	v_exp_f32_e32 v103, v103
	v_mfma_f32_32x32x16_bf16 v[80:95], v[234:237], v[164:167], v[80:95]
	v_exp_f32_e32 v104, v104
	v_exp_f32_e32 v105, v105
	v_exp_f32_e32 v106, v106
	v_exp_f32_e32 v107, v107
	s_waitcnt lgkmcnt(0)
; #define ALAS __attribute__((address_space(3)))
; __device__ __forceinline__ s16x4 vtr(const ALAS unsigned char* p) { return __builtin_bit_cast(s16x4, __builtin_amdgcn_ds_read_tr16_b64_v4i16((ALAS s16x4*)p)); }
; #define AMFMA(a, b, c) __builtin_amdgcn_mfma_f32_32x32x16_bf16((a), (b), (c), 0, 0, 0)
; template <bool SUB> __device__ __forceinline__ void attn_unit_r2(const AU& u, ALAS unsigned char* lds, float mb2) {
;     ...
;             R2_SOFT(Sa0, Sa1, paa, la);
;             R2_SOFT(Sb0, Sb1, pab, lb);
;     ...
; #pragma unroll
;             for (int ks = 0; ks < 4; ++ks) {
;                 const s16x4 lo0 = vtr(vb + ks * 16 * VP), hi0 = vtr(vb + (ks * 16 + 8) * VP), lo1 = vtr(vb + ks * 16 * VP + 64), hi1 = vtr(vb + (ks * 16 + 8) * VP + 64);
;                 const bf16x8 vf0 = __builtin_shufflevector(lo0, hi0, 0, 1, 2, 3, 4, 5, 6, 7), vf1 = __builtin_shufflevector(lo1, hi1, 0, 1, 2, 3, 4, 5, 6, 7);
;                 oa0 = AMFMA(paa[ks], vf0, oa0); oa1 = AMFMA(paa[ks], vf1, oa1); ob0 = AMFMA(pab[ks], vf0, ob0); ob1 = AMFMA(pab[ks], vf1, ob1);
;             }
;         }
;         if (t + 1 < NT) { *(ALAS u32x4*)(lds + (cur ^ 1) * KBUF + kl0) = rk; *(ALAS u32x4*)(lds + (cur ^ 1) * VBUF + vl) = rv; }
;         __syncthreads();
	v_mfma_f32_32x32x16_bf16 v[112:127], v[178:181], v[136:139], 0
	v_exp_f32_e32 v108, v108
	v_exp_f32_e32 v109, v109
	v_exp_f32_e32 v110, v110
	v_exp_f32_e32 v111, v111
	v_mfma_f32_32x32x16_bf16 v[112:127], v[182:185], v[140:143], v[112:127]
	v_cvt_pk_bf16_f32 v222, v96, v97
	v_cvt_pk_bf16_f32 v223, v98, v99
	v_cvt_pk_bf16_f32 v224, v100, v101
	v_cvt_pk_bf16_f32 v225, v102, v103
	v_exp_f32_e32 v80, v80
	v_exp_f32_e32 v81, v81
	v_mfma_f32_32x32x16_bf16 v[112:127], v[186:189], v[144:147], v[112:127]
	v_exp_f32_e32 v82, v82
	v_exp_f32_e32 v83, v83
	v_exp_f32_e32 v84, v84
	v_exp_f32_e32 v85, v85
	v_mfma_f32_32x32x16_bf16 v[112:127], v[190:193], v[148:151], v[112:127]
	v_exp_f32_e32 v86, v86
	v_exp_f32_e32 v87, v87
	v_cvt_pk_bf16_f32 v230, v104, v105
	v_cvt_pk_bf16_f32 v231, v106, v107
	v_cvt_pk_bf16_f32 v232, v108, v109
	v_cvt_pk_bf16_f32 v233, v110, v111
	v_mfma_f32_32x32x16_bf16 v[0:15], v[178:181], v[152:155], 0
	v_exp_f32_e32 v88, v88
	v_exp_f32_e32 v89, v89
	v_exp_f32_e32 v90, v90
	v_exp_f32_e32 v91, v91
	ds_read_b64_tr_b16 v[238:239], v221 offset:18432
	ds_read_b64_tr_b16 v[240:241], v221 offset:19584
	ds_read_b64_tr_b16 v[248:249], v221 offset:18496
	ds_read_b64_tr_b16 v[250:251], v221 offset:19648
	v_mfma_f32_32x32x16_bf16 v[0:15], v[182:185], v[156:159], v[0:15]
	v_exp_f32_e32 v92, v92
	v_exp_f32_e32 v93, v93
	v_exp_f32_e32 v94, v94
	v_exp_f32_e32 v95, v95
	v_mfma_f32_32x32x16_bf16 v[0:15], v[186:189], v[160:163], v[0:15]
	v_cvt_pk_bf16_f32 v226, v80, v81
	v_cvt_pk_bf16_f32 v227, v82, v83
	v_cvt_pk_bf16_f32 v228, v84, v85
	v_cvt_pk_bf16_f32 v229, v86, v87
	v_exp_f32_e32 v112, v112
	v_exp_f32_e32 v113, v113
	v_mfma_f32_32x32x16_bf16 v[0:15], v[190:193], v[164:167], v[0:15]
	v_exp_f32_e32 v114, v114
	v_exp_f32_e32 v115, v115
	v_exp_f32_e32 v116, v116
	v_exp_f32_e32 v117, v117
	ds_read_b64_tr_b16 v[194:195], v221 offset:20736
	ds_read_b64_tr_b16 v[196:197], v221 offset:21888
	ds_read_b64_tr_b16 v[210:211], v221 offset:20800
	ds_read_b64_tr_b16 v[212:213], v221 offset:21952
	s_waitcnt lgkmcnt(4)
	v_mfma_f32_32x32x16_bf16 v[48:63], v[222:225], v[238:241], v[48:63]
	v_exp_f32_e32 v118, v118
	v_exp_f32_e32 v119, v119
	v_exp_f32_e32 v120, v120
	v_exp_f32_e32 v121, v121
	v_mfma_f32_32x32x16_bf16 v[64:79], v[222:225], v[248:251], v[64:79]
	v_cvt_pk_bf16_f32 v234, v88, v89
	v_cvt_pk_bf16_f32 v235, v90, v91
	v_cvt_pk_bf16_f32 v236, v92, v93
	v_cvt_pk_bf16_f32 v237, v94, v95
	v_exp_f32_e32 v122, v122
	v_exp_f32_e32 v123, v123
	v_mfma_f32_32x32x16_bf16 v[16:31], v[226:229], v[238:241], v[16:31]
	v_exp_f32_e32 v124, v124
	v_exp_f32_e32 v125, v125
	v_exp_f32_e32 v126, v126
	v_exp_f32_e32 v127, v127
	v_mfma_f32_32x32x16_bf16 v[32:47], v[226:229], v[248:251], v[32:47]
	ds_read_b64_tr_b16 v[238:239], v221 offset:23040
	ds_read_b64_tr_b16 v[240:241], v221 offset:24192
	ds_read_b64_tr_b16 v[248:249], v221 offset:23104
	ds_read_b64_tr_b16 v[250:251], v221 offset:24256
	v_exp_f32_e32 v0, v0
	v_exp_f32_e32 v1, v1
	v_exp_f32_e32 v2, v2
	v_exp_f32_e32 v3, v3
	s_waitcnt vmcnt(0) lgkmcnt(4)
	v_mfma_f32_32x32x16_bf16 v[48:63], v[230:233], v[194:197], v[48:63]
	v_exp_f32_e32 v4, v4
	v_exp_f32_e32 v5, v5
	v_exp_f32_e32 v6, v6
	v_exp_f32_e32 v7, v7
	v_mfma_f32_32x32x16_bf16 v[64:79], v[230:233], v[210:213], v[64:79]
	v_cvt_pk_bf16_f32 v178, v112, v113
	v_cvt_pk_bf16_f32 v179, v114, v115
	v_cvt_pk_bf16_f32 v180, v116, v117
	v_cvt_pk_bf16_f32 v181, v118, v119
	v_exp_f32_e32 v8, v8
	v_exp_f32_e32 v9, v9
	v_mfma_f32_32x32x16_bf16 v[16:31], v[234:237], v[194:197], v[16:31]
	v_exp_f32_e32 v10, v10
	v_exp_f32_e32 v11, v11
	v_exp_f32_e32 v12, v12
	v_exp_f32_e32 v13, v13
	v_mfma_f32_32x32x16_bf16 v[32:47], v[234:237], v[210:213], v[32:47]
	ds_read_b64_tr_b16 v[194:195], v221 offset:25344
	ds_read_b64_tr_b16 v[196:197], v221 offset:26496
	ds_read_b64_tr_b16 v[210:211], v221 offset:25408
	ds_read_b64_tr_b16 v[212:213], v221 offset:26560
	v_exp_f32_e32 v14, v14
	v_exp_f32_e32 v15, v15
	v_cvt_pk_bf16_f32 v182, v0, v1
	v_cvt_pk_bf16_f32 v183, v2, v3
	v_cvt_pk_bf16_f32 v184, v4, v5
	v_cvt_pk_bf16_f32 v185, v6, v7
	v_cvt_pk_bf16_f32 v186, v120, v121
	v_cvt_pk_bf16_f32 v187, v122, v123
	v_cvt_pk_bf16_f32 v188, v124, v125
	v_cvt_pk_bf16_f32 v189, v126, v127
	v_cvt_pk_bf16_f32 v190, v8, v9
	v_cvt_pk_bf16_f32 v191, v10, v11
	v_cvt_pk_bf16_f32 v192, v12, v13
	v_cvt_pk_bf16_f32 v193, v14, v15
	ds_write_b128 v220, v[128:131] offset:9216
	ds_write_b128 v220, v[132:135] offset:27648
	s_waitcnt lgkmcnt(0)
	s_barrier

; #define ALAS __attribute__((address_space(3)))
; #define AMFMA(a, b, c) __builtin_amdgcn_mfma_f32_32x32x16_bf16((a), (b), (c), 0, 0, 0)
; template <bool SUB> __device__ __forceinline__ void attn_unit_r2(const AU& u, ALAS unsigned char* lds, float mb2) {
;     ...
;         if (t + 1 < NT) { const size_t ro = (size_t)(t + 1) * 64; rk = *(const u32x4*)(kg0 + ro * u.krs); rv = *(const u32x4*)(vg + ro * u.vrs); }
;         {
;             const ALAS unsigned char* kb = lds + cur * KBUF + r * KP + h * 16;
;             const ALAS unsigned char* vb = lds + V_OFF + cur * VBUF + (4 * h + ((lane & 15) >> 2)) * VP + ((lane >> 4) & 1) * 32 + (lane & 3) * 8;
;             f32x16 Sa0 = negm, Sa1 = negm, Sb0 = negm, Sb1 = negm;
; #pragma unroll
;             for (int d0 = 0; d0 < 4; ++d0) {
;                 const bf16x8 k0 = *(const ALAS bf16x8*)(kb + d0 * 32), k1 = *(const ALAS bf16x8*)(kb + 32 * KP + d0 * 32);
;                 Sa0 = AMFMA(k0, qa[d0], Sa0); Sa1 = AMFMA(k1, qa[d0], Sa1); Sb0 = AMFMA(k0, qb[d0], Sb0); Sb1 = AMFMA(k1, qb[d0], Sb1);
;             }
;             bf16x8 paa[4], pab[4];
.Lr2n_noloadB:
	ds_read_b128 v[222:225], v168 offset:9216
	ds_read_b128 v[226:229], v168 offset:9248
	ds_read_b128 v[230:233], v168 offset:9280
	ds_read_b128 v[234:237], v168 offset:9312
	v_mfma_f32_32x32x16_bf16 v[48:63], v[178:181], v[238:241], v[48:63]
	v_add_f32_e32 v172, v96, v172
	v_add_f32_e32 v173, v80, v173
	v_add_f32_e32 v172, v97, v172
	v_add_f32_e32 v173, v81, v173
	v_mfma_f32_32x32x16_bf16 v[64:79], v[178:181], v[248:251], v[64:79]
	v_add_f32_e32 v172, v98, v172
	v_add_f32_e32 v173, v82, v173
	v_add_f32_e32 v172, v99, v172
	v_add_f32_e32 v173, v83, v173
	ds_read_b128 v[178:181], v168 offset:13824
	v_mfma_f32_32x32x16_bf16 v[16:31], v[182:185], v[238:241], v[16:31]
	v_add_f32_e32 v172, v100, v172
	v_add_f32_e32 v173, v84, v173
	v_add_f32_e32 v172, v101, v172
	v_add_f32_e32 v173, v85, v173
	v_mfma_f32_32x32x16_bf16 v[32:47], v[182:185], v[248:251], v[32:47]
	v_add_f32_e32 v172, v102, v172
	v_add_f32_e32 v173, v86, v173
	v_add_f32_e32 v172, v103, v172
	v_add_f32_e32 v173, v87, v173
	ds_read_b128 v[182:185], v168 offset:13856
	v_mfma_f32_32x32x16_bf16 v[48:63], v[186:189], v[194:197], v[48:63]
	v_add_f32_e32 v172, v104, v172
	v_add_f32_e32 v173, v88, v173
	v_add_f32_e32 v172, v105, v172
	v_add_f32_e32 v173, v89, v173
	v_mfma_f32_32x32x16_bf16 v[64:79], v[186:189], v[210:213], v[64:79]
	v_add_f32_e32 v172, v106, v172
	v_add_f32_e32 v173, v90, v173
	v_add_f32_e32 v172, v107, v172
	v_add_f32_e32 v173, v91, v173
	ds_read_b128 v[186:189], v168 offset:13888
	v_mfma_f32_32x32x16_bf16 v[16:31], v[190:193], v[194:197], v[16:31]
	v_add_f32_e32 v172, v108, v172
	v_add_f32_e32 v173, v92, v173
	v_add_f32_e32 v172, v109, v172
	v_add_f32_e32 v173, v93, v173
	v_mfma_f32_32x32x16_bf16 v[32:47], v[190:193], v[210:213], v[32:47]
	v_add_f32_e32 v172, v110, v172
	v_add_f32_e32 v173, v94, v173
	v_add_f32_e32 v172, v111, v172
	v_add_f32_e32 v173, v95, v173
	ds_read_b128 v[190:193], v168 offset:13920
	s_waitcnt lgkmcnt(4)
	v_mfma_f32_32x32x16_bf16 v[96:111], v[222:225], v[136:139], 0
	v_lshl_add_u64 v[174:175], v[174:175], 0, s[12:13]
	v_add_f32_e32 v242, v112, v242
	v_add_f32_e32 v243, v0, v243
	v_add_f32_e32 v242, v113, v242
	v_add_f32_e32 v243, v1, v243
	v_add_f32_e32 v242, v114, v242
	v_mfma_f32_32x32x16_bf16 v[96:111], v[226:229], v[140:143], v[96:111]
	v_lshl_add_u64 v[176:177], v[176:177], 0, s[12:13]
	v_add_f32_e32 v243, v2, v243
	v_add_f32_e32 v242, v115, v242
	v_add_f32_e32 v243, v3, v243
	v_add_f32_e32 v242, v116, v242
	v_add_f32_e32 v243, v4, v243
	v_mfma_f32_32x32x16_bf16 v[96:111], v[230:233], v[144:147], v[96:111]
	v_add_f32_e32 v242, v117, v242
	v_add_f32_e32 v243, v5, v243
	v_add_f32_e32 v242, v118, v242
	v_add_f32_e32 v243, v6, v243
	v_add_f32_e32 v242, v119, v242
	v_add_f32_e32 v243, v7, v243
	v_mfma_f32_32x32x16_bf16 v[96:111], v[234:237], v[148:151], v[96:111]
	v_add_f32_e32 v242, v120, v242
	v_add_f32_e32 v243, v8, v243
	v_add_f32_e32 v242, v121, v242
	v_add_f32_e32 v243, v9, v243
	v_add_f32_e32 v242, v122, v242
	v_add_f32_e32 v243, v10, v243
	v_add_f32_e32 v242, v123, v242
	v_add_f32_e32 v243, v11, v243
	v_mfma_f32_32x32x16_bf16 v[80:95], v[222:225], v[152:155], 0
	v_add_f32_e32 v242, v124, v242
	v_add_f32_e32 v243, v12, v243
	v_add_f32_e32 v242, v125, v242
	v_add_f32_e32 v243, v13, v243
	v_add_f32_e32 v242, v126, v242
	v_add_f32_e32 v243, v14, v243
	v_add_f32_e32 v242, v127, v242
	v_add_f32_e32 v243, v15, v243
	v_mfma_f32_32x32x16_bf16 v[80:95], v[226:229], v[156:159], v[80:95]
	v_exp_f32_e32 v96, v96
	v_exp_f32_e32 v97, v97
	v_exp_f32_e32 v98, v98
	v_exp_f32_e32 v99, v99
	v_mfma_f32_32x32x16_bf16 v[80:95], v[230:233], v[160:163], v[80:95]
	v_exp_f32_e32 v100, v100
	v_exp_f32_e32 v101, v101
	v_exp_f32_e32 v102, v102
	v_exp_f32_e32 v103, v103
	v_mfma_f32_32x32x16_bf16 v[80:95], v[234:237], v[164:167], v[80:95]
	v_exp_f32_e32 v104, v104
	v_exp_f32_e32 v105, v105
	v_exp_f32_e32 v106, v106
	v_exp_f32_e32 v107, v107
	s_waitcnt lgkmcnt(0)
; #define ALAS __attribute__((address_space(3)))
; __device__ __forceinline__ s16x4 vtr(const ALAS unsigned char* p) { return __builtin_bit_cast(s16x4, __builtin_amdgcn_ds_read_tr16_b64_v4i16((ALAS s16x4*)p)); }
; #define AMFMA(a, b, c) __builtin_amdgcn_mfma_f32_32x32x16_bf16((a), (b), (c), 0, 0, 0)
; template <bool SUB> __device__ __forceinline__ void attn_unit_r2(const AU& u, ALAS unsigned char* lds, float mb2) {
;     ...
;             R2_SOFT(Sa0, Sa1, paa, la);
;             R2_SOFT(Sb0, Sb1, pab, lb);
;     ...
; #pragma unroll
;             for (int ks = 0; ks < 4; ++ks) {
;                 const s16x4 lo0 = vtr(vb + ks * 16 * VP), hi0 = vtr(vb + (ks * 16 + 8) * VP), lo1 = vtr(vb + ks * 16 * VP + 64), hi1 = vtr(vb + (ks * 16 + 8) * VP + 64);
;                 const bf16x8 vf0 = __builtin_shufflevector(lo0, hi0, 0, 1, 2, 3, 4, 5, 6, 7), vf1 = __builtin_shufflevector(lo1, hi1, 0, 1, 2, 3, 4, 5, 6, 7);
;                 oa0 = AMFMA(paa[ks], vf0, oa0); oa1 = AMFMA(paa[ks], vf1, oa1); ob0 = AMFMA(pab[ks], vf0, ob0); ob1 = AMFMA(pab[ks], vf1, ob1);
;             }
;         }
;         if (t + 1 < NT) { *(ALAS u32x4*)(lds + (cur ^ 1) * KBUF + kl0) = rk; *(ALAS u32x4*)(lds + (cur ^ 1) * VBUF + vl) = rv; }
	v_mfma_f32_32x32x16_bf16 v[112:127], v[178:181], v[136:139], 0
	v_exp_f32_e32 v108, v108
	v_exp_f32_e32 v109, v109
	v_exp_f32_e32 v110, v110
	v_exp_f32_e32 v111, v111
	v_mfma_f32_32x32x16_bf16 v[112:127], v[182:185], v[140:143], v[112:127]
	v_cvt_pk_bf16_f32 v222, v96, v97
	v_cvt_pk_bf16_f32 v223, v98, v99
	v_cvt_pk_bf16_f32 v224, v100, v101
	v_cvt_pk_bf16_f32 v225, v102, v103
	v_exp_f32_e32 v80, v80
	v_exp_f32_e32 v81, v81
	v_mfma_f32_32x32x16_bf16 v[112:127], v[186:189], v[144:147], v[112:127]
	v_exp_f32_e32 v82, v82
	v_exp_f32_e32 v83, v83
	v_exp_f32_e32 v84, v84
	v_exp_f32_e32 v85, v85
	v_mfma_f32_32x32x16_bf16 v[112:127], v[190:193], v[148:151], v[112:127]
	v_exp_f32_e32 v86, v86
	v_exp_f32_e32 v87, v87
	v_cvt_pk_bf16_f32 v230, v104, v105
	v_cvt_pk_bf16_f32 v231, v106, v107
	v_cvt_pk_bf16_f32 v232, v108, v109
	v_cvt_pk_bf16_f32 v233, v110, v111
	v_mfma_f32_32x32x16_bf16 v[0:15], v[178:181], v[152:155], 0
	v_exp_f32_e32 v88, v88
	v_exp_f32_e32 v89, v89
	v_exp_f32_e32 v90, v90
	v_exp_f32_e32 v91, v91
	ds_read_b64_tr_b16 v[238:239], v221 offset:27648
	ds_read_b64_tr_b16 v[240:241], v221 offset:28800
	ds_read_b64_tr_b16 v[248:249], v221 offset:27712
	ds_read_b64_tr_b16 v[250:251], v221 offset:28864
	v_mfma_f32_32x32x16_bf16 v[0:15], v[182:185], v[156:159], v[0:15]
	v_exp_f32_e32 v92, v92
	v_exp_f32_e32 v93, v93
	v_exp_f32_e32 v94, v94
	v_exp_f32_e32 v95, v95
	v_mfma_f32_32x32x16_bf16 v[0:15], v[186:189], v[160:163], v[0:15]
	v_cvt_pk_bf16_f32 v226, v80, v81
	v_cvt_pk_bf16_f32 v227, v82, v83
	v_cvt_pk_bf16_f32 v228, v84, v85
	v_cvt_pk_bf16_f32 v229, v86, v87
	v_exp_f32_e32 v112, v112
	v_exp_f32_e32 v113, v113
	v_mfma_f32_32x32x16_bf16 v[0:15], v[190:193], v[164:167], v[0:15]
	v_exp_f32_e32 v114, v114
	v_exp_f32_e32 v115, v115
	v_exp_f32_e32 v116, v116
	v_exp_f32_e32 v117, v117
	ds_read_b64_tr_b16 v[194:195], v221 offset:29952
	ds_read_b64_tr_b16 v[196:197], v221 offset:31104
	ds_read_b64_tr_b16 v[210:211], v221 offset:30016
	ds_read_b64_tr_b16 v[212:213], v221 offset:31168
	s_waitcnt lgkmcnt(4)
	v_mfma_f32_32x32x16_bf16 v[48:63], v[222:225], v[238:241], v[48:63]
	v_exp_f32_e32 v118, v118
	v_exp_f32_e32 v119, v119
	v_exp_f32_e32 v120, v120
	v_exp_f32_e32 v121, v121
	v_mfma_f32_32x32x16_bf16 v[64:79], v[222:225], v[248:251], v[64:79]
	v_cvt_pk_bf16_f32 v234, v88, v89
	v_cvt_pk_bf16_f32 v235, v90, v91
	v_cvt_pk_bf16_f32 v236, v92, v93
	v_cvt_pk_bf16_f32 v237, v94, v95
	v_exp_f32_e32 v122, v122
	v_exp_f32_e32 v123, v123
	v_mfma_f32_32x32x16_bf16 v[16:31], v[226:229], v[238:241], v[16:31]
	v_exp_f32_e32 v124, v124
	v_exp_f32_e32 v125, v125
	v_exp_f32_e32 v126, v126
	v_exp_f32_e32 v127, v127
	v_mfma_f32_32x32x16_bf16 v[32:47], v[226:229], v[248:251], v[32:47]
	ds_read_b64_tr_b16 v[238:239], v221 offset:32256
	ds_read_b64_tr_b16 v[240:241], v221 offset:33408
	ds_read_b64_tr_b16 v[248:249], v221 offset:32320
	ds_read_b64_tr_b16 v[250:251], v221 offset:33472
	v_exp_f32_e32 v0, v0
	v_exp_f32_e32 v1, v1
	v_exp_f32_e32 v2, v2
	v_exp_f32_e32 v3, v3
	s_waitcnt vmcnt(0) lgkmcnt(4)
	v_mfma_f32_32x32x16_bf16 v[48:63], v[230:233], v[194:197], v[48:63]
	v_exp_f32_e32 v4, v4
	v_exp_f32_e32 v5, v5
	v_exp_f32_e32 v6, v6
	v_exp_f32_e32 v7, v7
	v_mfma_f32_32x32x16_bf16 v[64:79], v[230:233], v[210:213], v[64:79]
	v_cvt_pk_bf16_f32 v178, v112, v113
	v_cvt_pk_bf16_f32 v179, v114, v115
	v_cvt_pk_bf16_f32 v180, v116, v117
	v_cvt_pk_bf16_f32 v181, v118, v119
	v_exp_f32_e32 v8, v8
	v_exp_f32_e32 v9, v9
	v_mfma_f32_32x32x16_bf16 v[16:31], v[234:237], v[194:197], v[16:31]
	v_exp_f32_e32 v10, v10
	v_exp_f32_e32 v11, v11
	v_exp_f32_e32 v12, v12
	v_exp_f32_e32 v13, v13
	s_andn2_b64 vcc, exec, s[54:55]
	v_mfma_f32_32x32x16_bf16 v[32:47], v[234:237], v[210:213], v[32:47]
	ds_read_b64_tr_b16 v[194:195], v221 offset:34560
	ds_read_b64_tr_b16 v[196:197], v221 offset:35712
	ds_read_b64_tr_b16 v[210:211], v221 offset:34624
	ds_read_b64_tr_b16 v[212:213], v221 offset:35776
	v_exp_f32_e32 v14, v14
	v_exp_f32_e32 v15, v15
	v_cvt_pk_bf16_f32 v182, v0, v1
	v_cvt_pk_bf16_f32 v183, v2, v3
	v_cvt_pk_bf16_f32 v184, v4, v5
	v_cvt_pk_bf16_f32 v185, v6, v7
	v_cvt_pk_bf16_f32 v186, v120, v121
	v_cvt_pk_bf16_f32 v187, v122, v123
	v_cvt_pk_bf16_f32 v188, v124, v125
	v_cvt_pk_bf16_f32 v189, v126, v127
	v_cvt_pk_bf16_f32 v190, v8, v9
	v_cvt_pk_bf16_f32 v191, v10, v11
	v_cvt_pk_bf16_f32 v192, v12, v13
	v_cvt_pk_bf16_f32 v193, v14, v15
	s_cbranch_vccnz .Lr2n_nowriteB
	ds_write_b128 v220, v[128:131] offset:0
	ds_write_b128 v220, v[132:135] offset:18432

; #define ALAS __attribute__((address_space(3)))
; __device__ __forceinline__ s16x4 vtr(const ALAS unsigned char* p) { return __builtin_bit_cast(s16x4, __builtin_amdgcn_ds_read_tr16_b64_v4i16((ALAS s16x4*)p)); }
; #define AMFMA(a, b, c) __builtin_amdgcn_mfma_f32_32x32x16_bf16((a), (b), (c), 0, 0, 0)
; template <bool SUB> __device__ __forceinline__ void attn_unit_r2b(const AU& u, ALAS unsigned char* lds, float mb2) {
;     ...
;         if (t + 1 < NT) { const size_t ro = (size_t)(t + 1) * 64; rk0 = *(const u32x4*)(kg0 + ro * u.krs); if (k2) rk1 = *(const u32x4*)(kg1 + ro * u.krs); rv = *(const u32x4*)(vg + ro * u.vrs); }
;         {
;             const ALAS unsigned char* kb = lds + cur * KBUF + r * KP + h * 16;
;             const ALAS unsigned char* vb = lds + V_OFF + cur * VBUF + (4 * h + ((lane & 15) >> 2)) * VP + ((lane >> 4) & 1) * 32 + (lane & 3) * 8;
;             bf16x8 paa[4], pab[4];
;             f32x16 Sa0, Sa1, Sb0, Sb1;
; #pragma unroll
;             for (int i = 0; i < 16; ++i) { Sa0[i] = 0.f; Sa1[i] = 0.f; Sb0[i] = 0.f; Sb1[i] = 0.f; }
; #pragma unroll
;             for (int d0 = 0; d0 < 6; ++d0) {
;                 const bf16x8 k0 = *(const ALAS bf16x8*)(kb + d0 * 32), k1 = *(const ALAS bf16x8*)(kb + 32 * KP + d0 * 32); const bf16x8 qbv = *(const ALAS bf16x8*)(qbl + d0 * 1024);
;                 Sa0 = AMFMA(k0, qa[d0], Sa0); Sa1 = AMFMA(k1, qa[d0], Sa1); Sb0 = AMFMA(k0, qbv, Sb0); Sb1 = AMFMA(k1, qbv, Sb1);
;                 if (d0 & 1) __builtin_amdgcn_sched_barrier(0);
;             }
;     ...
;             R2B_SOFT(Sa0, Sa1, paa, la);
;             __builtin_amdgcn_sched_barrier(0);
;             R2B_SOFT(Sb0, Sb1, pab, lb);
;     ...
; #pragma unroll
;             for (int ks = 0; ks < 4; ++ks) {
;                 const s16x4 lo0 = vtr(vb + ks * 16 * VP), hi0 = vtr(vb + (ks * 16 + 8) * VP), lo1 = vtr(vb + ks * 16 * VP + 64), hi1 = vtr(vb + (ks * 16 + 8) * VP + 64);
.Lr2b_topA:
	global_load_dwordx4 v[152:155], v[172:173], off
	s_cmp_eq_u64 s[40:41], 0
	s_cbranch_scc1 .Lr2b_nok2A
	global_load_dwordx4 v[156:159], v[174:175], off
.Lr2b_nok2A:
	global_load_dwordx4 v[160:163], v[166:167], off
	ds_read_b128 v[218:221], v168 offset:0
	ds_read_b128 v[222:225], v168 offset:32
	ds_read_b128 v[226:229], v168 offset:64
	ds_read_b128 v[230:233], v168 offset:96
	ds_read_b128 v[234:237], v168 offset:128
	ds_read_b128 v[238:241], v168 offset:160
	ds_read_b128 v[176:179], v193 offset:45056
	ds_read_b128 v[180:183], v193 offset:46080
	ds_read_b128 v[184:187], v193 offset:47104
	ds_read_b128 v[248:251], v193 offset:48128
	ds_read_b128 v[244:247], v193 offset:49152
	s_waitcnt lgkmcnt(5)
	v_mfma_f32_32x32x16_bf16 v[96:111], v[218:221], v[128:131], 0
	v_lshl_add_u64 v[166:167], v[166:167], 0, s[8:9]
	v_add_f32_e32 v242, v112, v242
	v_add_f32_e32 v243, v80, v243
	v_add_f32_e32 v242, v113, v242
	v_add_f32_e32 v243, v81, v243
	v_mfma_f32_32x32x16_bf16 v[96:111], v[222:225], v[132:135], v[96:111]
	v_lshl_add_u64 v[172:173], v[172:173], 0, s[12:13]
	v_add_f32_e32 v242, v114, v242
	v_add_f32_e32 v243, v82, v243
	v_add_f32_e32 v242, v115, v242
	v_add_f32_e32 v243, v83, v243
	v_mfma_f32_32x32x16_bf16 v[96:111], v[226:229], v[136:139], v[96:111]
	v_lshl_add_u64 v[174:175], v[174:175], 0, s[12:13]
	v_add_f32_e32 v242, v116, v242
	v_add_f32_e32 v243, v84, v243
	v_add_f32_e32 v242, v117, v242
	v_add_f32_e32 v243, v85, v243
	v_mfma_f32_32x32x16_bf16 v[96:111], v[230:233], v[140:143], v[96:111]
	v_add_f32_e32 v242, v118, v242
	v_add_f32_e32 v243, v86, v243
	v_add_f32_e32 v242, v119, v242
	v_add_f32_e32 v243, v87, v243
	v_add_f32_e32 v242, v120, v242
	v_mfma_f32_32x32x16_bf16 v[96:111], v[234:237], v[144:147], v[96:111]
	v_add_f32_e32 v243, v88, v243
	v_add_f32_e32 v242, v121, v242
	v_add_f32_e32 v243, v89, v243
	v_add_f32_e32 v242, v122, v242
	v_add_f32_e32 v243, v90, v243
	v_add_f32_e32 v242, v123, v242
	v_mfma_f32_32x32x16_bf16 v[96:111], v[238:241], v[148:151], v[96:111]
	v_add_f32_e32 v243, v91, v243
	v_add_f32_e32 v242, v124, v242
	v_add_f32_e32 v243, v92, v243
	v_add_f32_e32 v242, v125, v242
	v_add_f32_e32 v243, v93, v243
	v_add_f32_e32 v242, v126, v242
	s_waitcnt lgkmcnt(0)
	v_mfma_f32_32x32x16_bf16 v[64:79], v[218:221], v[176:179], 0
	ds_read_b128 v[176:179], v193 offset:50176
	ds_read_b128 v[218:221], v168 offset:6656
	v_add_f32_e32 v243, v94, v243
	v_add_f32_e32 v242, v127, v242
	v_add_f32_e32 v243, v95, v243
	v_mfma_f32_32x32x16_bf16 v[64:79], v[222:225], v[180:183], v[64:79]
	ds_read_b128 v[222:225], v168 offset:6688
	v_exp_f32_e32 v96, v96
	v_exp_f32_e32 v97, v97
	v_mfma_f32_32x32x16_bf16 v[64:79], v[226:229], v[184:187], v[64:79]
	ds_read_b128 v[226:229], v168 offset:6720
	v_exp_f32_e32 v98, v98
	v_exp_f32_e32 v99, v99
	v_mfma_f32_32x32x16_bf16 v[64:79], v[230:233], v[248:251], v[64:79]
	ds_read_b128 v[230:233], v168 offset:6752
	v_exp_f32_e32 v100, v100
	v_exp_f32_e32 v101, v101
	v_mfma_f32_32x32x16_bf16 v[64:79], v[234:237], v[244:247], v[64:79]
	ds_read_b128 v[234:237], v168 offset:6784
	v_exp_f32_e32 v102, v102
	v_exp_f32_e32 v103, v103
	s_waitcnt lgkmcnt(5)
	v_mfma_f32_32x32x16_bf16 v[64:79], v[238:241], v[176:179], v[64:79]
	ds_read_b128 v[238:241], v168 offset:6816
	ds_read_b128 v[176:179], v193 offset:45056
	v_exp_f32_e32 v104, v104
	v_exp_f32_e32 v105, v105
	v_exp_f32_e32 v106, v106
	v_exp_f32_e32 v107, v107
	s_waitcnt lgkmcnt(1)
	v_mfma_f32_32x32x16_bf16 v[112:127], v[218:221], v[128:131], 0
	v_exp_f32_e32 v108, v108
	v_exp_f32_e32 v109, v109
	v_exp_f32_e32 v110, v110
	v_exp_f32_e32 v111, v111
	v_mfma_f32_32x32x16_bf16 v[112:127], v[222:225], v[132:135], v[112:127]
	v_exp_f32_e32 v64, v64
	v_exp_f32_e32 v65, v65
	v_exp_f32_e32 v66, v66
	v_mfma_f32_32x32x16_bf16 v[112:127], v[226:229], v[136:139], v[112:127]
	v_exp_f32_e32 v67, v67
	v_exp_f32_e32 v68, v68
	v_exp_f32_e32 v69, v69
	v_mfma_f32_32x32x16_bf16 v[112:127], v[230:233], v[140:143], v[112:127]
	v_exp_f32_e32 v70, v70
	v_exp_f32_e32 v71, v71
	v_exp_f32_e32 v72, v72
	v_mfma_f32_32x32x16_bf16 v[112:127], v[234:237], v[144:147], v[112:127]
	v_exp_f32_e32 v73, v73
	v_exp_f32_e32 v74, v74
	v_exp_f32_e32 v75, v75
	v_mfma_f32_32x32x16_bf16 v[112:127], v[238:241], v[148:151], v[112:127]
	v_exp_f32_e32 v76, v76
	v_exp_f32_e32 v77, v77
	v_exp_f32_e32 v78, v78
	v_exp_f32_e32 v79, v79
	s_waitcnt lgkmcnt(0)
	v_mfma_f32_32x32x16_bf16 v[80:95], v[218:221], v[176:179], 0
	ds_read_b128 v[176:179], v193 offset:50176
	v_cvt_pk_bf16_f32 v218, v96, v97
	v_cvt_pk_bf16_f32 v219, v98, v99
	v_cvt_pk_bf16_f32 v220, v100, v101
	v_cvt_pk_bf16_f32 v221, v102, v103
	v_mfma_f32_32x32x16_bf16 v[80:95], v[222:225], v[180:183], v[80:95]
	v_cvt_pk_bf16_f32 v222, v64, v65
	v_cvt_pk_bf16_f32 v223, v66, v67
	v_cvt_pk_bf16_f32 v224, v68, v69
	v_cvt_pk_bf16_f32 v225, v70, v71
	v_exp_f32_e32 v112, v112
	v_exp_f32_e32 v113, v113
	v_mfma_f32_32x32x16_bf16 v[80:95], v[226:229], v[184:187], v[80:95]
	v_cvt_pk_bf16_f32 v226, v104, v105
	v_cvt_pk_bf16_f32 v227, v106, v107
	v_cvt_pk_bf16_f32 v228, v108, v109
	v_cvt_pk_bf16_f32 v229, v110, v111
	v_exp_f32_e32 v114, v114
	v_exp_f32_e32 v115, v115
	ds_read_b64_tr_b16 v[184:185], v197 offset:26624
	ds_read_b64_tr_b16 v[186:187], v197 offset:27776
	v_mfma_f32_32x32x16_bf16 v[80:95], v[230:233], v[248:251], v[80:95]
	v_cvt_pk_bf16_f32 v230, v72, v73
	v_cvt_pk_bf16_f32 v231, v74, v75
	v_cvt_pk_bf16_f32 v232, v76, v77
	v_cvt_pk_bf16_f32 v233, v78, v79
	v_exp_f32_e32 v116, v116
	v_exp_f32_e32 v117, v117
	ds_read_b64_tr_b16 v[248:249], v197 offset:26688
	ds_read_b64_tr_b16 v[250:251], v197 offset:27840
	v_mfma_f32_32x32x16_bf16 v[80:95], v[234:237], v[244:247], v[80:95]
	v_exp_f32_e32 v118, v118
	v_exp_f32_e32 v119, v119
	v_exp_f32_e32 v120, v120
	v_exp_f32_e32 v121, v121
	ds_read_b64_tr_b16 v[244:245], v197 offset:28928
	ds_read_b64_tr_b16 v[246:247], v197 offset:30080
	s_waitcnt lgkmcnt(2)
; #define ALAS __attribute__((address_space(3)))
; __device__ __forceinline__ s16x4 vtr(const ALAS unsigned char* p) { return __builtin_bit_cast(s16x4, __builtin_amdgcn_ds_read_tr16_b64_v4i16((ALAS s16x4*)p)); }
; #define AMFMA(a, b, c) __builtin_amdgcn_mfma_f32_32x32x16_bf16((a), (b), (c), 0, 0, 0)
; template <bool SUB> __device__ __forceinline__ void attn_unit_r2b(const AU& u, ALAS unsigned char* lds, float mb2) {
;     ...
;             R2B_SOFT(Sb0, Sb1, pab, lb);
;     ...
; #pragma unroll
;             for (int ks = 0; ks < 4; ++ks) {
;                 const s16x4 lo0 = vtr(vb + ks * 16 * VP), hi0 = vtr(vb + (ks * 16 + 8) * VP), lo1 = vtr(vb + ks * 16 * VP + 64), hi1 = vtr(vb + (ks * 16 + 8) * VP + 64);
;                 const bf16x8 vf0 = __builtin_shufflevector(lo0, hi0, 0, 1, 2, 3, 4, 5, 6, 7), vf1 = __builtin_shufflevector(lo1, hi1, 0, 1, 2, 3, 4, 5, 6, 7);
;                 oa0 = AMFMA(paa[ks], vf0, oa0); oa1 = AMFMA(paa[ks], vf1, oa1); ob0 = AMFMA(pab[ks], vf0, ob0); ob1 = AMFMA(pab[ks], vf1, ob1);
;             }
;         }
;         if (t + 1 < NT) { *(ALAS u32x4*)(lds + (cur ^ 1) * KBUF + kl0) = rk0; if (k2) *(ALAS u32x4*)(lds + (cur ^ 1) * KBUF + kl1) = rk1; *(ALAS u32x4*)(lds + (cur ^ 1) * VBUF + vl) = rv; }
;         __syncthreads();
	v_mfma_f32_32x32x16_bf16 v[80:95], v[238:241], v[176:179], v[80:95]
	v_exp_f32_e32 v122, v122
	v_exp_f32_e32 v123, v123
	v_exp_f32_e32 v124, v124
	v_exp_f32_e32 v125, v125
	v_mfma_f32_32x32x16_bf16 v[32:47], v[218:221], v[184:187], v[32:47]
	v_exp_f32_e32 v126, v126
	v_exp_f32_e32 v127, v127
	v_cvt_pk_bf16_f32 v234, v112, v113
	v_cvt_pk_bf16_f32 v235, v114, v115
	v_cvt_pk_bf16_f32 v236, v116, v117
	v_cvt_pk_bf16_f32 v237, v118, v119
	v_mfma_f32_32x32x16_bf16 v[48:63], v[218:221], v[248:251], v[48:63]
	v_exp_f32_e32 v80, v80
	v_exp_f32_e32 v81, v81
	v_exp_f32_e32 v82, v82
	v_exp_f32_e32 v83, v83
	v_mfma_f32_32x32x16_bf16 v[0:15], v[222:225], v[184:187], v[0:15]
	ds_read_b64_tr_b16 v[184:185], v197 offset:28992
	ds_read_b64_tr_b16 v[186:187], v197 offset:30144
	v_exp_f32_e32 v84, v84
	v_exp_f32_e32 v85, v85
	v_exp_f32_e32 v86, v86
	v_exp_f32_e32 v87, v87
	v_mfma_f32_32x32x16_bf16 v[16:31], v[222:225], v[248:251], v[16:31]
	ds_read_b64_tr_b16 v[248:249], v197 offset:31232
	ds_read_b64_tr_b16 v[250:251], v197 offset:32384
	v_exp_f32_e32 v88, v88
	v_exp_f32_e32 v89, v89
	v_exp_f32_e32 v90, v90
	v_exp_f32_e32 v91, v91
	s_waitcnt lgkmcnt(2)
	v_mfma_f32_32x32x16_bf16 v[32:47], v[226:229], v[244:247], v[32:47]
	v_exp_f32_e32 v92, v92
	v_exp_f32_e32 v93, v93
	v_exp_f32_e32 v94, v94
	v_exp_f32_e32 v95, v95
	v_mfma_f32_32x32x16_bf16 v[48:63], v[226:229], v[184:187], v[48:63]
	v_cvt_pk_bf16_f32 v176, v120, v121
	v_cvt_pk_bf16_f32 v177, v122, v123
	v_cvt_pk_bf16_f32 v178, v124, v125
	v_cvt_pk_bf16_f32 v179, v126, v127
	v_cvt_pk_bf16_f32 v238, v80, v81
	v_cvt_pk_bf16_f32 v239, v82, v83
	v_cvt_pk_bf16_f32 v240, v84, v85
	v_cvt_pk_bf16_f32 v241, v86, v87
	v_mfma_f32_32x32x16_bf16 v[0:15], v[230:233], v[244:247], v[0:15]
	ds_read_b64_tr_b16 v[244:245], v197 offset:31296
	ds_read_b64_tr_b16 v[246:247], v197 offset:32448
	v_cvt_pk_bf16_f32 v180, v88, v89
	v_cvt_pk_bf16_f32 v181, v90, v91
	v_cvt_pk_bf16_f32 v182, v92, v93
	v_cvt_pk_bf16_f32 v183, v94, v95
	v_add_f32_e32 v164, v96, v164
	v_add_f32_e32 v165, v64, v165
	v_add_f32_e32 v164, v97, v164
	v_mfma_f32_32x32x16_bf16 v[16:31], v[230:233], v[184:187], v[16:31]
	ds_read_b64_tr_b16 v[184:185], v197 offset:33536
	ds_read_b64_tr_b16 v[186:187], v197 offset:34688
	v_add_f32_e32 v165, v65, v165
	v_add_f32_e32 v164, v98, v164
	v_add_f32_e32 v165, v66, v165
	v_add_f32_e32 v164, v99, v164
	v_add_f32_e32 v165, v67, v165
	s_waitcnt lgkmcnt(2)
	v_mfma_f32_32x32x16_bf16 v[32:47], v[234:237], v[248:251], v[32:47]
	v_add_f32_e32 v164, v100, v164
	v_add_f32_e32 v165, v68, v165
	v_add_f32_e32 v164, v101, v164
	v_add_f32_e32 v165, v69, v165
	v_add_f32_e32 v164, v102, v164
	v_add_f32_e32 v165, v70, v165
	v_mfma_f32_32x32x16_bf16 v[48:63], v[234:237], v[244:247], v[48:63]
	v_add_f32_e32 v164, v103, v164
	v_add_f32_e32 v165, v71, v165
	v_add_f32_e32 v164, v104, v164
	v_add_f32_e32 v165, v72, v165
	v_add_f32_e32 v164, v105, v164
	v_add_f32_e32 v165, v73, v165
	v_mfma_f32_32x32x16_bf16 v[0:15], v[238:241], v[248:251], v[0:15]
	ds_read_b64_tr_b16 v[248:249], v197 offset:33600
	ds_read_b64_tr_b16 v[250:251], v197 offset:34752
	v_add_f32_e32 v164, v106, v164
	v_add_f32_e32 v165, v74, v165
	v_add_f32_e32 v164, v107, v164
	v_add_f32_e32 v165, v75, v165
	v_add_f32_e32 v164, v108, v164
	v_mfma_f32_32x32x16_bf16 v[16:31], v[238:241], v[244:247], v[16:31]
	v_add_f32_e32 v165, v76, v165
	v_add_f32_e32 v164, v109, v164
	v_add_f32_e32 v165, v77, v165
	v_add_f32_e32 v164, v110, v164
	v_add_f32_e32 v165, v78, v165
	v_add_f32_e32 v164, v111, v164
	s_waitcnt vmcnt(0) lgkmcnt(0)
	v_mfma_f32_32x32x16_bf16 v[32:47], v[176:179], v[184:187], v[32:47]
	v_add_f32_e32 v165, v79, v165
	v_mfma_f32_32x32x16_bf16 v[48:63], v[176:179], v[248:251], v[48:63]
	ds_write_b128 v194, v[152:155] offset:13312
	s_cmp_eq_u64 s[40:41], 0
	s_cbranch_scc1 .Lr2b_nok2wA
	ds_write_b128 v195, v[156:159] offset:13312
.Lr2b_nok2wA:
	ds_write_b128 v196, v[160:163] offset:35840
	v_mfma_f32_32x32x16_bf16 v[0:15], v[180:183], v[184:187], v[0:15]
	v_mfma_f32_32x32x16_bf16 v[16:31], v[180:183], v[248:251], v[16:31]
	s_waitcnt lgkmcnt(0)
	s_barrier
.Lr2b_topB:
	s_add_i32 s61, s62, 2
	s_cmp_lt_u32 s61, s28
	s_cselect_b64 s[56:57], -1, 0
	s_cbranch_scc0 .Lr2b_noloadB
	global_load_dwordx4 v[152:155], v[172:173], off
	s_cmp_eq_u64 s[40:41], 0
	s_cbranch_scc1 .Lr2b_nok2B
	global_load_dwordx4 v[156:159], v[174:175], off
.Lr2b_nok2B:
	global_load_dwordx4 v[160:163], v[166:167], off
; #define ALAS __attribute__((address_space(3)))
; #define AMFMA(a, b, c) __builtin_amdgcn_mfma_f32_32x32x16_bf16((a), (b), (c), 0, 0, 0)
; template <bool SUB> __device__ __forceinline__ void attn_unit_r2b(const AU& u, ALAS unsigned char* lds, float mb2) {
;     ...
;         if (t + 1 < NT) { const size_t ro = (size_t)(t + 1) * 64; rk0 = *(const u32x4*)(kg0 + ro * u.krs); if (k2) rk1 = *(const u32x4*)(kg1 + ro * u.krs); rv = *(const u32x4*)(vg + ro * u.vrs); }
;         {
;             const ALAS unsigned char* kb = lds + cur * KBUF + r * KP + h * 16;
;             const ALAS unsigned char* vb = lds + V_OFF + cur * VBUF + (4 * h + ((lane & 15) >> 2)) * VP + ((lane >> 4) & 1) * 32 + (lane & 3) * 8;
;             bf16x8 paa[4], pab[4];
;             f32x16 Sa0, Sa1, Sb0, Sb1;
; #pragma unroll
;             for (int i = 0; i < 16; ++i) { Sa0[i] = 0.f; Sa1[i] = 0.f; Sb0[i] = 0.f; Sb1[i] = 0.f; }
; #pragma unroll
;             for (int d0 = 0; d0 < 6; ++d0) {
;                 const bf16x8 k0 = *(const ALAS bf16x8*)(kb + d0 * 32), k1 = *(const ALAS bf16x8*)(kb + 32 * KP + d0 * 32); const bf16x8 qbv = *(const ALAS bf16x8*)(qbl + d0 * 1024);
;                 Sa0 = AMFMA(k0, qa[d0], Sa0); Sa1 = AMFMA(k1, qa[d0], Sa1); Sb0 = AMFMA(k0, qbv, Sb0); Sb1 = AMFMA(k1, qbv, Sb1);
;                 if (d0 & 1) __builtin_amdgcn_sched_barrier(0);
;             }
;     ...
;             R2B_SOFT(Sa0, Sa1, paa, la);
.Lr2b_noloadB:
	ds_read_b128 v[218:221], v168 offset:13312
	ds_read_b128 v[222:225], v168 offset:13344
	ds_read_b128 v[226:229], v168 offset:13376
	ds_read_b128 v[230:233], v168 offset:13408
	ds_read_b128 v[234:237], v168 offset:13440
	ds_read_b128 v[238:241], v168 offset:13472
	ds_read_b128 v[176:179], v193 offset:45056
	ds_read_b128 v[180:183], v193 offset:46080
	ds_read_b128 v[184:187], v193 offset:47104
	ds_read_b128 v[248:251], v193 offset:48128
	ds_read_b128 v[244:247], v193 offset:49152
	s_waitcnt lgkmcnt(5)
	v_mfma_f32_32x32x16_bf16 v[96:111], v[218:221], v[128:131], 0
	v_lshl_add_u64 v[166:167], v[166:167], 0, s[8:9]
	v_add_f32_e32 v242, v112, v242
	v_add_f32_e32 v243, v80, v243
	v_add_f32_e32 v242, v113, v242
	v_add_f32_e32 v243, v81, v243
	v_mfma_f32_32x32x16_bf16 v[96:111], v[222:225], v[132:135], v[96:111]
	v_lshl_add_u64 v[172:173], v[172:173], 0, s[12:13]
	v_add_f32_e32 v242, v114, v242
	v_add_f32_e32 v243, v82, v243
	v_add_f32_e32 v242, v115, v242
	v_add_f32_e32 v243, v83, v243
	v_mfma_f32_32x32x16_bf16 v[96:111], v[226:229], v[136:139], v[96:111]
	v_lshl_add_u64 v[174:175], v[174:175], 0, s[12:13]
	v_add_f32_e32 v242, v116, v242
	v_add_f32_e32 v243, v84, v243
	v_add_f32_e32 v242, v117, v242
	v_add_f32_e32 v243, v85, v243
	v_mfma_f32_32x32x16_bf16 v[96:111], v[230:233], v[140:143], v[96:111]
	v_add_f32_e32 v242, v118, v242
	v_add_f32_e32 v243, v86, v243
	v_add_f32_e32 v242, v119, v242
	v_add_f32_e32 v243, v87, v243
	v_add_f32_e32 v242, v120, v242
	v_mfma_f32_32x32x16_bf16 v[96:111], v[234:237], v[144:147], v[96:111]
	v_add_f32_e32 v243, v88, v243
	v_add_f32_e32 v242, v121, v242
	v_add_f32_e32 v243, v89, v243
	v_add_f32_e32 v242, v122, v242
	v_add_f32_e32 v243, v90, v243
	v_add_f32_e32 v242, v123, v242
	v_mfma_f32_32x32x16_bf16 v[96:111], v[238:241], v[148:151], v[96:111]
	v_add_f32_e32 v243, v91, v243
	v_add_f32_e32 v242, v124, v242
	v_add_f32_e32 v243, v92, v243
	v_add_f32_e32 v242, v125, v242
	v_add_f32_e32 v243, v93, v243
	v_add_f32_e32 v242, v126, v242
	s_waitcnt lgkmcnt(0)
	v_mfma_f32_32x32x16_bf16 v[64:79], v[218:221], v[176:179], 0
	ds_read_b128 v[176:179], v193 offset:50176
	ds_read_b128 v[218:221], v168 offset:19968
	v_add_f32_e32 v243, v94, v243
	v_add_f32_e32 v242, v127, v242
	v_add_f32_e32 v243, v95, v243
	v_mfma_f32_32x32x16_bf16 v[64:79], v[222:225], v[180:183], v[64:79]
	ds_read_b128 v[222:225], v168 offset:20000
	v_exp_f32_e32 v96, v96
	v_exp_f32_e32 v97, v97
	v_mfma_f32_32x32x16_bf16 v[64:79], v[226:229], v[184:187], v[64:79]
	ds_read_b128 v[226:229], v168 offset:20032
	v_exp_f32_e32 v98, v98
	v_exp_f32_e32 v99, v99
	v_mfma_f32_32x32x16_bf16 v[64:79], v[230:233], v[248:251], v[64:79]
	ds_read_b128 v[230:233], v168 offset:20064
	v_exp_f32_e32 v100, v100
	v_exp_f32_e32 v101, v101
	v_mfma_f32_32x32x16_bf16 v[64:79], v[234:237], v[244:247], v[64:79]
	ds_read_b128 v[234:237], v168 offset:20096
	v_exp_f32_e32 v102, v102
	v_exp_f32_e32 v103, v103
	s_waitcnt lgkmcnt(5)
	v_mfma_f32_32x32x16_bf16 v[64:79], v[238:241], v[176:179], v[64:79]
	ds_read_b128 v[238:241], v168 offset:20128
	ds_read_b128 v[176:179], v193 offset:45056
	v_exp_f32_e32 v104, v104
	v_exp_f32_e32 v105, v105
	v_exp_f32_e32 v106, v106
	v_exp_f32_e32 v107, v107
	s_waitcnt lgkmcnt(1)
	v_mfma_f32_32x32x16_bf16 v[112:127], v[218:221], v[128:131], 0
	v_exp_f32_e32 v108, v108
	v_exp_f32_e32 v109, v109
	v_exp_f32_e32 v110, v110
	v_exp_f32_e32 v111, v111
	v_mfma_f32_32x32x16_bf16 v[112:127], v[222:225], v[132:135], v[112:127]
	v_exp_f32_e32 v64, v64
	v_exp_f32_e32 v65, v65
	v_exp_f32_e32 v66, v66
	v_mfma_f32_32x32x16_bf16 v[112:127], v[226:229], v[136:139], v[112:127]
	v_exp_f32_e32 v67, v67
	v_exp_f32_e32 v68, v68
	v_exp_f32_e32 v69, v69
	v_mfma_f32_32x32x16_bf16 v[112:127], v[230:233], v[140:143], v[112:127]
	v_exp_f32_e32 v70, v70
	v_exp_f32_e32 v71, v71
	v_exp_f32_e32 v72, v72
	v_mfma_f32_32x32x16_bf16 v[112:127], v[234:237], v[144:147], v[112:127]
	v_exp_f32_e32 v73, v73
	v_exp_f32_e32 v74, v74
	v_exp_f32_e32 v75, v75
	v_mfma_f32_32x32x16_bf16 v[112:127], v[238:241], v[148:151], v[112:127]
	v_exp_f32_e32 v76, v76
	v_exp_f32_e32 v77, v77
	v_exp_f32_e32 v78, v78
	v_exp_f32_e32 v79, v79
	s_waitcnt lgkmcnt(0)
; #define ALAS __attribute__((address_space(3)))
; __device__ __forceinline__ s16x4 vtr(const ALAS unsigned char* p) { return __builtin_bit_cast(s16x4, __builtin_amdgcn_ds_read_tr16_b64_v4i16((ALAS s16x4*)p)); }
; #define AMFMA(a, b, c) __builtin_amdgcn_mfma_f32_32x32x16_bf16((a), (b), (c), 0, 0, 0)
; template <bool SUB> __device__ __forceinline__ void attn_unit_r2b(const AU& u, ALAS unsigned char* lds, float mb2) {
;     ...
;             R2B_SOFT(Sa0, Sa1, paa, la);
;             __builtin_amdgcn_sched_barrier(0);
;             R2B_SOFT(Sb0, Sb1, pab, lb);
;     ...
; #pragma unroll
;             for (int ks = 0; ks < 4; ++ks) {
;                 const s16x4 lo0 = vtr(vb + ks * 16 * VP), hi0 = vtr(vb + (ks * 16 + 8) * VP), lo1 = vtr(vb + ks * 16 * VP + 64), hi1 = vtr(vb + (ks * 16 + 8) * VP + 64);
;                 const bf16x8 vf0 = __builtin_shufflevector(lo0, hi0, 0, 1, 2, 3, 4, 5, 6, 7), vf1 = __builtin_shufflevector(lo1, hi1, 0, 1, 2, 3, 4, 5, 6, 7);
;                 oa0 = AMFMA(paa[ks], vf0, oa0); oa1 = AMFMA(paa[ks], vf1, oa1); ob0 = AMFMA(pab[ks], vf0, ob0); ob1 = AMFMA(pab[ks], vf1, ob1);
;             }
;         }
;         if (t + 1 < NT) { *(ALAS u32x4*)(lds + (cur ^ 1) * KBUF + kl0) = rk0; if (k2) *(ALAS u32x4*)(lds + (cur ^ 1) * KBUF + kl1) = rk1; *(ALAS u32x4*)(lds + (cur ^ 1) * VBUF + vl) = rv; }
	v_mfma_f32_32x32x16_bf16 v[80:95], v[218:221], v[176:179], 0
	ds_read_b128 v[176:179], v193 offset:50176
	v_cvt_pk_bf16_f32 v218, v96, v97
	v_cvt_pk_bf16_f32 v219, v98, v99
	v_cvt_pk_bf16_f32 v220, v100, v101
	v_cvt_pk_bf16_f32 v221, v102, v103
	v_mfma_f32_32x32x16_bf16 v[80:95], v[222:225], v[180:183], v[80:95]
	v_cvt_pk_bf16_f32 v222, v64, v65
	v_cvt_pk_bf16_f32 v223, v66, v67
	v_cvt_pk_bf16_f32 v224, v68, v69
	v_cvt_pk_bf16_f32 v225, v70, v71
	v_exp_f32_e32 v112, v112
	v_exp_f32_e32 v113, v113
	v_mfma_f32_32x32x16_bf16 v[80:95], v[226:229], v[184:187], v[80:95]
	v_cvt_pk_bf16_f32 v226, v104, v105
	v_cvt_pk_bf16_f32 v227, v106, v107
	v_cvt_pk_bf16_f32 v228, v108, v109
	v_cvt_pk_bf16_f32 v229, v110, v111
	v_exp_f32_e32 v114, v114
	v_exp_f32_e32 v115, v115
	ds_read_b64_tr_b16 v[184:185], v197 offset:35840
	ds_read_b64_tr_b16 v[186:187], v197 offset:36992
	v_mfma_f32_32x32x16_bf16 v[80:95], v[230:233], v[248:251], v[80:95]
	v_cvt_pk_bf16_f32 v230, v72, v73
	v_cvt_pk_bf16_f32 v231, v74, v75
	v_cvt_pk_bf16_f32 v232, v76, v77
	v_cvt_pk_bf16_f32 v233, v78, v79
	v_exp_f32_e32 v116, v116
	v_exp_f32_e32 v117, v117
	ds_read_b64_tr_b16 v[248:249], v197 offset:35904
	ds_read_b64_tr_b16 v[250:251], v197 offset:37056
	v_mfma_f32_32x32x16_bf16 v[80:95], v[234:237], v[244:247], v[80:95]
	v_exp_f32_e32 v118, v118
	v_exp_f32_e32 v119, v119
	v_exp_f32_e32 v120, v120
	v_exp_f32_e32 v121, v121
	ds_read_b64_tr_b16 v[244:245], v197 offset:38144
	ds_read_b64_tr_b16 v[246:247], v197 offset:39296
	s_waitcnt lgkmcnt(2)
	v_mfma_f32_32x32x16_bf16 v[80:95], v[238:241], v[176:179], v[80:95]
	v_exp_f32_e32 v122, v122
	v_exp_f32_e32 v123, v123
	v_exp_f32_e32 v124, v124
	v_exp_f32_e32 v125, v125
	v_mfma_f32_32x32x16_bf16 v[32:47], v[218:221], v[184:187], v[32:47]
	v_exp_f32_e32 v126, v126
	v_exp_f32_e32 v127, v127
	v_cvt_pk_bf16_f32 v234, v112, v113
	v_cvt_pk_bf16_f32 v235, v114, v115
	v_cvt_pk_bf16_f32 v236, v116, v117
	v_cvt_pk_bf16_f32 v237, v118, v119
	v_mfma_f32_32x32x16_bf16 v[48:63], v[218:221], v[248:251], v[48:63]
	v_exp_f32_e32 v80, v80
	v_exp_f32_e32 v81, v81
	v_exp_f32_e32 v82, v82
	v_exp_f32_e32 v83, v83
	v_mfma_f32_32x32x16_bf16 v[0:15], v[222:225], v[184:187], v[0:15]
	ds_read_b64_tr_b16 v[184:185], v197 offset:38208
	ds_read_b64_tr_b16 v[186:187], v197 offset:39360
	v_exp_f32_e32 v84, v84
	v_exp_f32_e32 v85, v85
	v_exp_f32_e32 v86, v86
	v_exp_f32_e32 v87, v87
	v_mfma_f32_32x32x16_bf16 v[16:31], v[222:225], v[248:251], v[16:31]
	ds_read_b64_tr_b16 v[248:249], v197 offset:40448
	ds_read_b64_tr_b16 v[250:251], v197 offset:41600
	v_exp_f32_e32 v88, v88
	v_exp_f32_e32 v89, v89
	v_exp_f32_e32 v90, v90
	v_exp_f32_e32 v91, v91
	s_waitcnt lgkmcnt(2)
	v_mfma_f32_32x32x16_bf16 v[32:47], v[226:229], v[244:247], v[32:47]
	v_exp_f32_e32 v92, v92
	v_exp_f32_e32 v93, v93
	v_exp_f32_e32 v94, v94
	v_exp_f32_e32 v95, v95
	v_mfma_f32_32x32x16_bf16 v[48:63], v[226:229], v[184:187], v[48:63]
	v_cvt_pk_bf16_f32 v176, v120, v121
	v_cvt_pk_bf16_f32 v177, v122, v123
	v_cvt_pk_bf16_f32 v178, v124, v125
	v_cvt_pk_bf16_f32 v179, v126, v127
	v_cvt_pk_bf16_f32 v238, v80, v81
	v_cvt_pk_bf16_f32 v239, v82, v83
	v_cvt_pk_bf16_f32 v240, v84, v85
	v_cvt_pk_bf16_f32 v241, v86, v87
	v_mfma_f32_32x32x16_bf16 v[0:15], v[230:233], v[244:247], v[0:15]
	ds_read_b64_tr_b16 v[244:245], v197 offset:40512
	ds_read_b64_tr_b16 v[246:247], v197 offset:41664
	v_cvt_pk_bf16_f32 v180, v88, v89
	v_cvt_pk_bf16_f32 v181, v90, v91
	v_cvt_pk_bf16_f32 v182, v92, v93
	v_cvt_pk_bf16_f32 v183, v94, v95
	v_add_f32_e32 v164, v96, v164
	v_add_f32_e32 v165, v64, v165
	v_add_f32_e32 v164, v97, v164
	v_mfma_f32_32x32x16_bf16 v[16:31], v[230:233], v[184:187], v[16:31]
	ds_read_b64_tr_b16 v[184:185], v197 offset:42752
	ds_read_b64_tr_b16 v[186:187], v197 offset:43904
	v_add_f32_e32 v165, v65, v165
	v_add_f32_e32 v164, v98, v164
	v_add_f32_e32 v165, v66, v165
	v_add_f32_e32 v164, v99, v164
	v_add_f32_e32 v165, v67, v165
	s_waitcnt lgkmcnt(2)
	v_mfma_f32_32x32x16_bf16 v[32:47], v[234:237], v[248:251], v[32:47]
	v_add_f32_e32 v164, v100, v164
	v_add_f32_e32 v165, v68, v165
	v_add_f32_e32 v164, v101, v164
	v_add_f32_e32 v165, v69, v165
	v_add_f32_e32 v164, v102, v164
	v_add_f32_e32 v165, v70, v165
	v_mfma_f32_32x32x16_bf16 v[48:63], v[234:237], v[244:247], v[48:63]
	v_add_f32_e32 v164, v103, v164
	v_add_f32_e32 v165, v71, v165
	v_add_f32_e32 v164, v104, v164
	v_add_f32_e32 v165, v72, v165
	v_add_f32_e32 v164, v105, v164
	v_add_f32_e32 v165, v73, v165
	v_mfma_f32_32x32x16_bf16 v[0:15], v[238:241], v[248:251], v[0:15]
	ds_read_b64_tr_b16 v[248:249], v197 offset:42816
	ds_read_b64_tr_b16 v[250:251], v197 offset:43968
	v_add_f32_e32 v164, v106, v164
	v_add_f32_e32 v165, v74, v165
	v_add_f32_e32 v164, v107, v164
	v_add_f32_e32 v165, v75, v165
	v_add_f32_e32 v164, v108, v164
	v_mfma_f32_32x32x16_bf16 v[16:31], v[238:241], v[244:247], v[16:31]
	v_add_f32_e32 v165, v76, v165
	v_add_f32_e32 v164, v109, v164
	v_add_f32_e32 v165, v77, v165
	v_add_f32_e32 v164, v110, v164
	v_add_f32_e32 v165, v78, v165
	v_add_f32_e32 v164, v111, v164
	s_waitcnt vmcnt(0) lgkmcnt(0)
	v_mfma_f32_32x32x16_bf16 v[32:47], v[176:179], v[184:187], v[32:47]
	v_add_f32_e32 v165, v79, v165
	s_andn2_b64 vcc, exec, s[56:57]
	v_mfma_f32_32x32x16_bf16 v[48:63], v[176:179], v[248:251], v[48:63]
	s_cbranch_vccnz .Lr2b_nowriteB
	ds_write_b128 v194, v[152:155] offset:0
	s_cmp_eq_u64 s[40:41], 0
	s_cbranch_scc1 .Lr2b_nok2wB
	ds_write_b128 v195, v[156:159] offset:0
.Lr2b_nok2wB:
	ds_write_b128 v196, v[160:163] offset:26624
